# v21 + GEMM accumulator zeroing between units with 64-bit moves (63 v_mov_b64 instead of 126 v_mov_b32 per unit)
# speedup vs baseline: 1.0066x; 1.0022x over previous
; #define PG8_WAIT_V(n) asm volatile("s_waitcnt vmcnt(" #n ")" ::: "memory")
; #define PG8_WAIT_L(n) asm volatile("s_waitcnt lgkmcnt(" #n ")" ::: "memory")
; template <class Epi, bool ALIGN_EPI>
; __device__ __forceinline__ void gemm_phase(LAS unsigned char* lds, const Gemm g, const StaticOrder& S, const Epi& E) {
;     ...
;         const bool has_next = S.next(ui + 1, nxt);
;         const char* nA = has_next ? (const char*)g.A + (size_t)nxt.pm * tstepA : cA; const char* nB = has_next ? (const char*)g.Bt + (size_t)nxt.pn * tstepB : cB;
;         for (int t = 0; t < nt; t += 2) {
;             const bool last = (t == nt - 2);
;             const char* a1 = cA + (size_t)(t + 1) * kstep;
;             const char* a2 = last ? nA : cA + (size_t)(t + 2) * kstep; const char* b2 = last ? nB : cB + (size_t)(t + 2) * kstep;
;             const char* a3 = a2 + kstep; const char* b3 = b2 + kstep;
;             PG8_LDB(B0, 0, 0); PG8_LDB(B1, 0, 1); PG8_SCHED; PG8_LDA(At, 0, 0); PG8_STAGE(PG8_SA(1, 1), a1 + hstepA, voffA);
;             PG8_WAIT_V(8); PG8_WAIT_L(0); PG8_BAR; PG8_MMA(0, 0, At, B0); PG8_MMA(0, 1, At, B1); PG8_BAR; PG8_SCHED;
;             PG8_LDA(At, 0, 1); PG8_STAGE(PG8_SB(0, 0), b2, voffB); PG8_STAGE(PG8_SB(0, 1), b2 + hstepB, voffB); PG8_STAGE(PG8_SA(0, 0), a2, voffA);
;             PG8_WAIT_V(8); PG8_WAIT_L(0); PG8_BAR; PG8_MMA(1, 0, At, B0); PG8_MMA(1, 1, At, B1); PG8_BAR; PG8_SCHED;
;             PG8_LDB(B0, 1, 0); PG8_LDB(B1, 1, 1); PG8_SCHED; PG8_LDA(At, 1, 0); PG8_STAGE(PG8_SA(0, 1), a2 + hstepA, voffA);
;             PG8_WAIT_V(8); PG8_WAIT_L(0); PG8_BAR; PG8_MMA(0, 0, At, B0); PG8_MMA(0, 1, At, B1); PG8_BAR; PG8_SCHED;
;             PG8_LDA(At, 1, 1); PG8_STAGE(PG8_SB(1, 0), b3, voffB); PG8_STAGE(PG8_SB(1, 1), b3 + hstepB, voffB); PG8_STAGE(PG8_SA(1, 0), a3, voffA);
;             PG8_WAIT_V(8); PG8_WAIT_L(0); PG8_BAR; PG8_MMA(1, 0, At, B0); PG8_MMA(1, 1, At, B1); PG8_BAR; PG8_SCHED;
;         }
;         if constexpr (ALIGN_EPI) { if (wr == 0) PG8_BAR; }
;         E(acc, cur, wr, wc, fr, fq);
;         if (!has_next) break;
; #pragma unroll
;         for (int a = 0; a < 2; ++a)
; #pragma unroll
;             for (int b = 0; b < 2; ++b)
; #pragma unroll
;                 for (int m = 0; m < 4; ++m)
; #pragma unroll
;                     for (int n = 0; n < 2; ++n) acc[a][b][m][n] = (f32x4){0.f, 0.f, 0.f, 0.f};
.LBB0_1261:
	s_ashr_i32 s57, s56, 31
	s_lshl_b64 s[16:17], s[56:57], 19
	s_add_u32 s16, s8, s16
	s_addc_u32 s17, s9, s17
	s_and_b64 s[18:19], s[40:41], exec
	s_cselect_b32 s24, s17, s21
	s_cselect_b32 s25, s16, s20
	s_ashr_i32 s61, s60, 31
	s_lshl_b64 s[18:19], s[60:61], 19
	s_add_u32 s18, s80, s18
	v_readlane_b32 s28, v251, 51
	s_addc_u32 s19, s28, s19
	s_and_b64 s[28:29], s[40:41], exec
	s_cselect_b32 s28, s19, s23
	s_cselect_b32 s29, s18, s22
	s_add_u32 s46, s22, 0x100
	s_addc_u32 s47, s23, 0
	s_add_u32 s20, s20, 0x40080
	v_mov_b32_e32 v0, 0
	s_addc_u32 s21, s21, 0
	s_mov_b32 s54, -2
	v_mov_b32_e32 v1, v0
	v_mov_b64_e32 v[2:3], 0
	v_mov_b64_e32 v[10:11], 0
	v_mov_b64_e32 v[12:13], 0
	v_mov_b64_e32 v[18:19], 0
	v_mov_b64_e32 v[20:21], 0
	v_mov_b64_e32 v[26:27], 0
	v_mov_b64_e32 v[28:29], 0
	v_mov_b64_e32 v[34:35], 0
	v_mov_b64_e32 v[36:37], 0
	v_mov_b64_e32 v[42:43], 0
	v_mov_b64_e32 v[44:45], 0
	v_mov_b64_e32 v[50:51], 0
	v_mov_b64_e32 v[52:53], 0
	v_mov_b64_e32 v[58:59], 0
	v_mov_b64_e32 v[60:61], 0
	v_mov_b64_e32 v[6:7], 0
	v_mov_b64_e32 v[8:9], 0
	v_mov_b64_e32 v[14:15], 0
	v_mov_b64_e32 v[16:17], 0
	v_mov_b64_e32 v[22:23], 0
	v_mov_b64_e32 v[24:25], 0
	v_mov_b64_e32 v[30:31], 0
	v_mov_b64_e32 v[32:33], 0
	v_mov_b64_e32 v[38:39], 0
	v_mov_b64_e32 v[40:41], 0
	v_mov_b64_e32 v[46:47], 0
	v_mov_b64_e32 v[48:49], 0
	v_mov_b64_e32 v[54:55], 0
	v_mov_b64_e32 v[56:57], 0
	v_mov_b64_e32 v[62:63], 0
	v_mov_b64_e32 v[64:65], 0
	v_mov_b64_e32 v[66:67], 0
	v_mov_b64_e32 v[68:69], 0
	v_mov_b64_e32 v[74:75], 0
	v_mov_b64_e32 v[76:77], 0
	v_mov_b64_e32 v[82:83], 0
	v_mov_b64_e32 v[84:85], 0
	v_mov_b64_e32 v[90:91], 0
	v_mov_b64_e32 v[92:93], 0
	s_waitcnt vmcnt(0)
	v_mov_b64_e32 v[98:99], 0
	v_mov_b64_e32 v[100:101], 0
	v_mov_b64_e32 v[106:107], 0
	v_mov_b64_e32 v[108:109], 0
	v_mov_b64_e32 v[114:115], 0
	v_mov_b64_e32 v[116:117], 0
	v_mov_b64_e32 v[122:123], 0
	v_mov_b64_e32 v[124:125], 0
	v_mov_b64_e32 v[70:71], 0
	v_mov_b64_e32 v[72:73], 0
	v_mov_b64_e32 v[78:79], 0
	v_mov_b64_e32 v[80:81], 0
	v_mov_b64_e32 v[86:87], 0
	v_mov_b64_e32 v[88:89], 0
	v_mov_b64_e32 v[94:95], 0
	v_mov_b64_e32 v[96:97], 0
	v_mov_b64_e32 v[102:103], 0
	v_mov_b64_e32 v[104:105], 0
	v_mov_b64_e32 v[110:111], 0
	v_mov_b64_e32 v[112:113], 0
	v_mov_b64_e32 v[118:119], 0
	v_mov_b64_e32 v[120:121], 0
	v_mov_b64_e32 v[126:127], 0
	v_mov_b64_e32 v[128:129], 0

; template <class Epi, bool ALIGN_EPI>
; __device__ __forceinline__ void gemm_phase(LAS unsigned char* lds, const Gemm g, const StaticOrder& S, const Epi& E) {
;     ...
;         for (int a = 0; a < 2; ++a)
; #pragma unroll
;             for (int b = 0; b < 2; ++b)
; #pragma unroll
;                 for (int m = 0; m < 4; ++m)
; #pragma unroll
;                     for (int n = 0; n < 2; ++n) acc[a][b][m][n] = (f32x4){0.f, 0.f, 0.f, 0.f};
.LBB0_1291:
	s_add_u32 s28, s96, 0x100
	s_addc_u32 s29, s97, 0
	s_add_u32 s44, s50, 0x80
	v_mov_b32_e32 v0, 0
	s_addc_u32 s45, s51, 0
	s_mov_b32 s50, 0
	v_mov_b32_e32 v1, v0
	v_mov_b64_e32 v[2:3], 0
	v_mov_b64_e32 v[6:7], 0
	v_mov_b64_e32 v[8:9], 0
	v_mov_b64_e32 v[14:15], 0
	v_mov_b64_e32 v[16:17], 0
	v_mov_b64_e32 v[22:23], 0
	v_mov_b64_e32 v[24:25], 0
	v_mov_b64_e32 v[34:35], 0
	v_mov_b64_e32 v[36:37], 0
	v_mov_b64_e32 v[38:39], 0
	v_mov_b64_e32 v[40:41], 0
	v_mov_b64_e32 v[50:51], 0
	v_mov_b64_e32 v[52:53], 0
	v_mov_b64_e32 v[54:55], 0
	v_mov_b64_e32 v[56:57], 0
	v_mov_b64_e32 v[10:11], 0
	v_mov_b64_e32 v[12:13], 0
	v_mov_b64_e32 v[18:19], 0
	v_mov_b64_e32 v[20:21], 0
	v_mov_b64_e32 v[26:27], 0
	v_mov_b64_e32 v[28:29], 0
	v_mov_b64_e32 v[30:31], 0
	v_mov_b64_e32 v[32:33], 0
	v_mov_b64_e32 v[42:43], 0
	v_mov_b64_e32 v[44:45], 0
	v_mov_b64_e32 v[46:47], 0
	v_mov_b64_e32 v[48:49], 0
	v_mov_b64_e32 v[58:59], 0
	v_mov_b64_e32 v[60:61], 0
	v_mov_b64_e32 v[62:63], 0
	v_mov_b64_e32 v[64:65], 0
	v_mov_b64_e32 v[66:67], 0
	v_mov_b64_e32 v[68:69], 0
	v_mov_b64_e32 v[70:71], 0
	v_mov_b64_e32 v[72:73], 0
	v_mov_b64_e32 v[82:83], 0
	v_mov_b64_e32 v[84:85], 0
	v_mov_b64_e32 v[86:87], 0
	v_mov_b64_e32 v[88:89], 0
	s_waitcnt vmcnt(0)
	v_mov_b64_e32 v[98:99], 0
	v_mov_b64_e32 v[100:101], 0
	v_mov_b64_e32 v[102:103], 0
	v_mov_b64_e32 v[104:105], 0
	v_mov_b64_e32 v[114:115], 0
	v_mov_b64_e32 v[116:117], 0
	v_mov_b64_e32 v[118:119], 0
	v_mov_b64_e32 v[120:121], 0
	v_mov_b64_e32 v[74:75], 0
	v_mov_b64_e32 v[76:77], 0
	v_mov_b64_e32 v[78:79], 0
	v_mov_b64_e32 v[80:81], 0
	v_mov_b64_e32 v[90:91], 0
	v_mov_b64_e32 v[92:93], 0
	v_mov_b64_e32 v[94:95], 0
	v_mov_b64_e32 v[96:97], 0
	v_mov_b64_e32 v[106:107], 0
	v_mov_b64_e32 v[108:109], 0
	v_mov_b64_e32 v[110:111], 0
	v_mov_b64_e32 v[112:113], 0
	v_mov_b64_e32 v[122:123], 0
	v_mov_b64_e32 v[124:125], 0
	v_mov_b64_e32 v[126:127], 0
	v_mov_b64_e32 v[128:129], 0

; #define PG8_WAIT_V(n) asm volatile("s_waitcnt vmcnt(" #n ")" ::: "memory")
; #define PG8_WAIT_L(n) asm volatile("s_waitcnt lgkmcnt(" #n ")" ::: "memory")
; template <class Epi, bool ALIGN_EPI>
; __device__ __forceinline__ void gemm_phase(LAS unsigned char* lds, const Gemm g, const StaticOrder& S, const Epi& E) {
;     ...
;         const bool has_next = S.next(ui + 1, nxt);
;         const char* nA = has_next ? (const char*)g.A + (size_t)nxt.pm * tstepA : cA; const char* nB = has_next ? (const char*)g.Bt + (size_t)nxt.pn * tstepB : cB;
;         for (int t = 0; t < nt; t += 2) {
;             const bool last = (t == nt - 2);
;             const char* a1 = cA + (size_t)(t + 1) * kstep;
;             const char* a2 = last ? nA : cA + (size_t)(t + 2) * kstep; const char* b2 = last ? nB : cB + (size_t)(t + 2) * kstep;
;             const char* a3 = a2 + kstep; const char* b3 = b2 + kstep;
;             PG8_LDB(B0, 0, 0); PG8_LDB(B1, 0, 1); PG8_SCHED; PG8_LDA(At, 0, 0); PG8_STAGE(PG8_SA(1, 1), a1 + hstepA, voffA);
;             PG8_WAIT_V(8); PG8_WAIT_L(0); PG8_BAR; PG8_MMA(0, 0, At, B0); PG8_MMA(0, 1, At, B1); PG8_BAR; PG8_SCHED;
;             PG8_LDA(At, 0, 1); PG8_STAGE(PG8_SB(0, 0), b2, voffB); PG8_STAGE(PG8_SB(0, 1), b2 + hstepB, voffB); PG8_STAGE(PG8_SA(0, 0), a2, voffA);
;             PG8_WAIT_V(8); PG8_WAIT_L(0); PG8_BAR; PG8_MMA(1, 0, At, B0); PG8_MMA(1, 1, At, B1); PG8_BAR; PG8_SCHED;
;             PG8_LDB(B0, 1, 0); PG8_LDB(B1, 1, 1); PG8_SCHED; PG8_LDA(At, 1, 0); PG8_STAGE(PG8_SA(0, 1), a2 + hstepA, voffA);
;             PG8_WAIT_V(8); PG8_WAIT_L(0); PG8_BAR; PG8_MMA(0, 0, At, B0); PG8_MMA(0, 1, At, B1); PG8_BAR; PG8_SCHED;
;             PG8_LDA(At, 1, 1); PG8_STAGE(PG8_SB(1, 0), b3, voffB); PG8_STAGE(PG8_SB(1, 1), b3 + hstepB, voffB); PG8_STAGE(PG8_SA(1, 0), a3, voffA);
;             PG8_WAIT_V(8); PG8_WAIT_L(0); PG8_BAR; PG8_MMA(1, 0, At, B0); PG8_MMA(1, 1, At, B1); PG8_BAR; PG8_SCHED;
;         }
;         if constexpr (ALIGN_EPI) { if (wr == 0) PG8_BAR; }
;         E(acc, cur, wr, wc, fr, fq);
;         if (!has_next) break;
; #pragma unroll
;         for (int a = 0; a < 2; ++a)
; #pragma unroll
;             for (int b = 0; b < 2; ++b)
; #pragma unroll
;                 for (int m = 0; m < 4; ++m)
; #pragma unroll
;                     for (int n = 0; n < 2; ++n) acc[a][b][m][n] = (f32x4){0.f, 0.f, 0.f, 0.f};
.LBB0_1363:
	s_ashr_i32 s45, s44, 31
	s_lshl_b64 s[48:49], s[44:45], 18
	s_add_u32 s48, s7, s48
	s_addc_u32 s49, s4, s49
	s_and_b64 s[56:57], s[40:41], exec
	s_cselect_b32 s43, s49, s97
	s_cselect_b32 s45, s48, s96
	s_ashr_i32 s23, s22, 31
	s_lshl_b64 s[56:57], s[22:23], 18
	s_add_u32 s56, s46, s56
	s_addc_u32 s57, s47, s57
	s_and_b64 s[68:69], s[40:41], exec
	s_cselect_b32 s23, s57, s51
	s_cselect_b32 s61, s56, s50
	s_add_u32 s64, s50, 0x100
	s_addc_u32 s70, s51, 0
	s_add_u32 s96, s96, 0x20080
	v_mov_b32_e32 v0, 0
	s_addc_u32 s97, s97, 0
	s_mov_b32 s71, -2
	v_mov_b32_e32 v1, v0
	v_mov_b64_e32 v[2:3], 0
	v_mov_b64_e32 v[6:7], 0
	v_mov_b64_e32 v[8:9], 0
	v_mov_b64_e32 v[14:15], 0
	v_mov_b64_e32 v[16:17], 0
	v_mov_b64_e32 v[22:23], 0
	v_mov_b64_e32 v[24:25], 0
	v_mov_b64_e32 v[34:35], 0
	v_mov_b64_e32 v[36:37], 0
	v_mov_b64_e32 v[38:39], 0
	v_mov_b64_e32 v[40:41], 0
	v_mov_b64_e32 v[50:51], 0
	v_mov_b64_e32 v[52:53], 0
	v_mov_b64_e32 v[54:55], 0
	v_mov_b64_e32 v[56:57], 0
	v_mov_b64_e32 v[10:11], 0
	v_mov_b64_e32 v[12:13], 0
	v_mov_b64_e32 v[18:19], 0
	v_mov_b64_e32 v[20:21], 0
	v_mov_b64_e32 v[26:27], 0
	v_mov_b64_e32 v[28:29], 0
	v_mov_b64_e32 v[30:31], 0
	v_mov_b64_e32 v[32:33], 0
	v_mov_b64_e32 v[42:43], 0
	v_mov_b64_e32 v[44:45], 0
	v_mov_b64_e32 v[46:47], 0
	v_mov_b64_e32 v[48:49], 0
	v_mov_b64_e32 v[58:59], 0
	v_mov_b64_e32 v[60:61], 0
	v_mov_b64_e32 v[62:63], 0
	v_mov_b64_e32 v[64:65], 0
	v_mov_b64_e32 v[66:67], 0
	v_mov_b64_e32 v[68:69], 0
	v_mov_b64_e32 v[70:71], 0
	v_mov_b64_e32 v[72:73], 0
	v_mov_b64_e32 v[82:83], 0
	v_mov_b64_e32 v[84:85], 0
	v_mov_b64_e32 v[86:87], 0
	v_mov_b64_e32 v[88:89], 0
	s_waitcnt vmcnt(0)
	v_mov_b64_e32 v[98:99], 0
	v_mov_b64_e32 v[100:101], 0
	v_mov_b64_e32 v[102:103], 0
	v_mov_b64_e32 v[104:105], 0
	v_mov_b64_e32 v[114:115], 0
	v_mov_b64_e32 v[116:117], 0
	v_mov_b64_e32 v[118:119], 0
	v_mov_b64_e32 v[120:121], 0
	v_mov_b64_e32 v[74:75], 0
	v_mov_b64_e32 v[76:77], 0
	v_mov_b64_e32 v[78:79], 0
	v_mov_b64_e32 v[80:81], 0
	v_mov_b64_e32 v[90:91], 0
	v_mov_b64_e32 v[92:93], 0
	v_mov_b64_e32 v[94:95], 0
	v_mov_b64_e32 v[96:97], 0
	v_mov_b64_e32 v[106:107], 0
	v_mov_b64_e32 v[108:109], 0
	v_mov_b64_e32 v[110:111], 0
	v_mov_b64_e32 v[112:113], 0
	v_mov_b64_e32 v[122:123], 0
	v_mov_b64_e32 v[124:125], 0
	v_mov_b64_e32 v[126:127], 0
	v_mov_b64_e32 v[128:129], 0

; template <class Epi, bool ALIGN_EPI>
; __device__ __forceinline__ void gemm_phase(LAS unsigned char* lds, const Gemm g, const StaticOrder& S, const Epi& E) {
;     ...
;         for (int a = 0; a < 2; ++a)
; #pragma unroll
;             for (int b = 0; b < 2; ++b)
; #pragma unroll
;                 for (int m = 0; m < 4; ++m)
; #pragma unroll
;                     for (int n = 0; n < 2; ++n) acc[a][b][m][n] = (f32x4){0.f, 0.f, 0.f, 0.f};
.LBB0_1426:
	s_add_u32 s56, s56, 0x100
	v_mov_b32_e32 v0, 0
	s_addc_u32 s57, s57, 0
	s_mov_b32 s50, 0
	v_mov_b32_e32 v1, v0
	v_mov_b64_e32 v[2:3], 0
	v_mov_b64_e32 v[6:7], 0
	v_mov_b64_e32 v[8:9], 0
	v_mov_b64_e32 v[18:19], 0
	v_mov_b64_e32 v[20:21], 0
	v_mov_b64_e32 v[22:23], 0
	v_mov_b64_e32 v[24:25], 0
	v_mov_b64_e32 v[34:35], 0
	v_mov_b64_e32 v[36:37], 0
	v_mov_b64_e32 v[38:39], 0
	v_mov_b64_e32 v[40:41], 0
	v_mov_b64_e32 v[50:51], 0
	v_mov_b64_e32 v[52:53], 0
	v_mov_b64_e32 v[54:55], 0
	v_mov_b64_e32 v[56:57], 0
	v_mov_b64_e32 v[10:11], 0
	v_mov_b64_e32 v[12:13], 0
	v_mov_b64_e32 v[14:15], 0
	v_mov_b64_e32 v[16:17], 0
	v_mov_b64_e32 v[26:27], 0
	v_mov_b64_e32 v[28:29], 0
	v_mov_b64_e32 v[30:31], 0
	v_mov_b64_e32 v[32:33], 0
	v_mov_b64_e32 v[42:43], 0
	v_mov_b64_e32 v[44:45], 0
	v_mov_b64_e32 v[46:47], 0
	v_mov_b64_e32 v[48:49], 0
	v_mov_b64_e32 v[58:59], 0
	v_mov_b64_e32 v[60:61], 0
	v_mov_b64_e32 v[62:63], 0
	v_mov_b64_e32 v[64:65], 0
	v_mov_b64_e32 v[66:67], 0
	v_mov_b64_e32 v[68:69], 0
	v_mov_b64_e32 v[70:71], 0
	v_mov_b64_e32 v[72:73], 0
	v_mov_b64_e32 v[82:83], 0
	v_mov_b64_e32 v[84:85], 0
	v_mov_b64_e32 v[86:87], 0
	v_mov_b64_e32 v[88:89], 0
	v_mov_b64_e32 v[98:99], 0
	v_mov_b64_e32 v[100:101], 0
	v_mov_b64_e32 v[102:103], 0
	v_mov_b64_e32 v[104:105], 0
	v_mov_b64_e32 v[114:115], 0
	v_mov_b64_e32 v[116:117], 0
	v_mov_b64_e32 v[118:119], 0
	v_mov_b64_e32 v[120:121], 0
	v_mov_b64_e32 v[74:75], 0
	v_mov_b64_e32 v[76:77], 0
	v_mov_b64_e32 v[78:79], 0
	v_mov_b64_e32 v[80:81], 0
	v_mov_b64_e32 v[90:91], 0
	v_mov_b64_e32 v[92:93], 0
	v_mov_b64_e32 v[94:95], 0
	v_mov_b64_e32 v[96:97], 0
	v_mov_b64_e32 v[106:107], 0
	v_mov_b64_e32 v[108:109], 0
	v_mov_b64_e32 v[110:111], 0
	v_mov_b64_e32 v[112:113], 0
	v_mov_b64_e32 v[122:123], 0
	v_mov_b64_e32 v[124:125], 0
	v_mov_b64_e32 v[126:127], 0
	v_mov_b64_e32 v[128:129], 0

; #define PG8_WAIT_V(n) asm volatile("s_waitcnt vmcnt(" #n ")" ::: "memory")
; #define PG8_WAIT_L(n) asm volatile("s_waitcnt lgkmcnt(" #n ")" ::: "memory")
; template <class Epi, bool ALIGN_EPI>
; __device__ __forceinline__ void gemm_phase(LAS unsigned char* lds, const Gemm g, const StaticOrder& S, const Epi& E) {
;     ...
;         const bool has_next = S.next(ui + 1, nxt);
;         const char* nA = has_next ? (const char*)g.A + (size_t)nxt.pm * tstepA : cA; const char* nB = has_next ? (const char*)g.Bt + (size_t)nxt.pn * tstepB : cB;
;         for (int t = 0; t < nt; t += 2) {
;             const bool last = (t == nt - 2);
;             const char* a1 = cA + (size_t)(t + 1) * kstep;
;             const char* a2 = last ? nA : cA + (size_t)(t + 2) * kstep; const char* b2 = last ? nB : cB + (size_t)(t + 2) * kstep;
;             const char* a3 = a2 + kstep; const char* b3 = b2 + kstep;
;             PG8_LDB(B0, 0, 0); PG8_LDB(B1, 0, 1); PG8_SCHED; PG8_LDA(At, 0, 0); PG8_STAGE(PG8_SA(1, 1), a1 + hstepA, voffA);
;             PG8_WAIT_V(8); PG8_WAIT_L(0); PG8_BAR; PG8_MMA(0, 0, At, B0); PG8_MMA(0, 1, At, B1); PG8_BAR; PG8_SCHED;
;             PG8_LDA(At, 0, 1); PG8_STAGE(PG8_SB(0, 0), b2, voffB); PG8_STAGE(PG8_SB(0, 1), b2 + hstepB, voffB); PG8_STAGE(PG8_SA(0, 0), a2, voffA);
;             PG8_WAIT_V(8); PG8_WAIT_L(0); PG8_BAR; PG8_MMA(1, 0, At, B0); PG8_MMA(1, 1, At, B1); PG8_BAR; PG8_SCHED;
;             PG8_LDB(B0, 1, 0); PG8_LDB(B1, 1, 1); PG8_SCHED; PG8_LDA(At, 1, 0); PG8_STAGE(PG8_SA(0, 1), a2 + hstepA, voffA);
;             PG8_WAIT_V(8); PG8_WAIT_L(0); PG8_BAR; PG8_MMA(0, 0, At, B0); PG8_MMA(0, 1, At, B1); PG8_BAR; PG8_SCHED;
;             PG8_LDA(At, 1, 1); PG8_STAGE(PG8_SB(1, 0), b3, voffB); PG8_STAGE(PG8_SB(1, 1), b3 + hstepB, voffB); PG8_STAGE(PG8_SA(1, 0), a3, voffA);
;             PG8_WAIT_V(8); PG8_WAIT_L(0); PG8_BAR; PG8_MMA(1, 0, At, B0); PG8_MMA(1, 1, At, B1); PG8_BAR; PG8_SCHED;
;         }
;         if constexpr (ALIGN_EPI) { if (wr == 0) PG8_BAR; }
;         E(acc, cur, wr, wc, fr, fq);
;         if (!has_next) break;
; #pragma unroll
;         for (int a = 0; a < 2; ++a)
; #pragma unroll
;             for (int b = 0; b < 2; ++b)
; #pragma unroll
;                 for (int m = 0; m < 4; ++m)
; #pragma unroll
;                     for (int n = 0; n < 2; ++n) acc[a][b][m][n] = (f32x4){0.f, 0.f, 0.f, 0.f};
.LBB0_1482:
	s_ashr_i32 s45, s44, 31
	s_lshl_b64 s[24:25], s[44:45], 19
	s_add_u32 s48, s8, s24
	s_addc_u32 s49, s9, s25
	s_and_b64 s[24:25], s[40:41], exec
	s_cselect_b32 s7, s49, s51
	s_cselect_b32 s21, s48, s50
	s_ashr_i32 s19, s18, 31
	s_lshl_b64 s[24:25], s[18:19], 19
	s_add_u32 s56, s5, s24
	s_addc_u32 s57, s53, s25
	s_and_b64 s[24:25], s[40:41], exec
	s_cselect_b32 s19, s57, s43
	s_cselect_b32 s23, s56, s42
	s_add_u32 s24, s42, 0x100
	s_addc_u32 s25, s43, 0
	s_add_u32 s42, s50, 0x40080
	v_mov_b32_e32 v0, 0
	s_addc_u32 s43, s51, 0
	s_mov_b32 s28, -2
	v_mov_b32_e32 v1, v0
	v_mov_b64_e32 v[2:3], 0
	v_mov_b64_e32 v[6:7], 0
	v_mov_b64_e32 v[8:9], 0
	v_mov_b64_e32 v[18:19], 0
	v_mov_b64_e32 v[20:21], 0
	v_mov_b64_e32 v[22:23], 0
	v_mov_b64_e32 v[24:25], 0
	v_mov_b64_e32 v[34:35], 0
	v_mov_b64_e32 v[36:37], 0
	v_mov_b64_e32 v[38:39], 0
	v_mov_b64_e32 v[40:41], 0
	v_mov_b64_e32 v[50:51], 0
	v_mov_b64_e32 v[52:53], 0
	v_mov_b64_e32 v[54:55], 0
	v_mov_b64_e32 v[56:57], 0
	v_mov_b64_e32 v[10:11], 0
	v_mov_b64_e32 v[12:13], 0
	v_mov_b64_e32 v[14:15], 0
	v_mov_b64_e32 v[16:17], 0
	v_mov_b64_e32 v[26:27], 0
	v_mov_b64_e32 v[28:29], 0
	v_mov_b64_e32 v[30:31], 0
	v_mov_b64_e32 v[32:33], 0
	v_mov_b64_e32 v[42:43], 0
	v_mov_b64_e32 v[44:45], 0
	v_mov_b64_e32 v[46:47], 0
	v_mov_b64_e32 v[48:49], 0
	v_mov_b64_e32 v[58:59], 0
	v_mov_b64_e32 v[60:61], 0
	v_mov_b64_e32 v[62:63], 0
	v_mov_b64_e32 v[64:65], 0
	v_mov_b64_e32 v[66:67], 0
	v_mov_b64_e32 v[68:69], 0
	v_mov_b64_e32 v[70:71], 0
	v_mov_b64_e32 v[72:73], 0
	v_mov_b64_e32 v[82:83], 0
	v_mov_b64_e32 v[84:85], 0
	v_mov_b64_e32 v[86:87], 0
	v_mov_b64_e32 v[88:89], 0
	v_mov_b64_e32 v[98:99], 0
	v_mov_b64_e32 v[100:101], 0
	v_mov_b64_e32 v[102:103], 0
	v_mov_b64_e32 v[104:105], 0
	v_mov_b64_e32 v[114:115], 0
	v_mov_b64_e32 v[116:117], 0
	v_mov_b64_e32 v[118:119], 0
	v_mov_b64_e32 v[120:121], 0
	v_mov_b64_e32 v[74:75], 0
	v_mov_b64_e32 v[76:77], 0
	v_mov_b64_e32 v[78:79], 0
	v_mov_b64_e32 v[80:81], 0
	v_mov_b64_e32 v[90:91], 0
	v_mov_b64_e32 v[92:93], 0
	v_mov_b64_e32 v[94:95], 0
	v_mov_b64_e32 v[96:97], 0
	v_mov_b64_e32 v[106:107], 0
	v_mov_b64_e32 v[108:109], 0
	v_mov_b64_e32 v[110:111], 0
	v_mov_b64_e32 v[112:113], 0
	v_mov_b64_e32 v[122:123], 0
	v_mov_b64_e32 v[124:125], 0
	v_mov_b64_e32 v[126:127], 0
	v_mov_b64_e32 v[128:129], 0
